# rwkv_prep: parameters hoisted, row loads two iterations ahead, class branches by constant exec masks
# speedup vs baseline: 1.0048x; 1.0048x over previous
.LBB0_1029:
	s_mov_b64 s[4:5], s[0:1]
	s_mov_b32 s10, s2
	v_mov_b32_e32 v0, v154
	s_load_dwordx2 s[14:15], s[0:1], 0x138
	s_load_dwordx2 s[8:9], s[0:1], 0x88
	v_lshrrev_b32_e32 v40, 5, v154
	v_lshl_add_u32 v40, s2, 4, v40
	v_and_b32_e32 v41, 31, v154
	v_lshlrev_b32_e32 v41, 3, v41
	v_mul_u32_u24_e32 v42, 0x1e00, v40
	v_lshl_add_u32 v42, v41, 1, v42
	v_add_u32_e32 v43, 0x1000, v42
	v_lshlrev_b32_e32 v44, 9, v40
	v_lshl_add_u32 v44, v41, 1, v44
	v_or_b32_e32 v45, 0x600, v41
	v_lshlrev_b32_e32 v45, 2, v45
	v_and_b32_e32 v46, 0x7ff, v40
	v_cmp_ne_u32_e64 s[26:27], 0, v46
	s_mov_b32 s28, 0xff
	s_mov_b32 s29, 0xff
	s_mov_b32 s30, 0xffff0000
	s_mov_b32 s31, 0xffff0000
	s_waitcnt lgkmcnt(0)
	global_load_dwordx4 v[32:35], v45, s[8:9]
	global_load_dwordx4 v[36:39], v45, s[8:9] offset:16
	s_add_u32 s10, s14, 0x4300000
	s_addc_u32 s11, s15, 0
	global_load_dwordx4 v[0:3], v43, s[10:11] offset:3072
	global_load_dwordx4 v[4:7], v42, s[10:11] offset:-512
	s_add_u32 s10, s14, 0x6100000
	s_addc_u32 s11, s15, 0
	global_load_dwordx4 v[8:11], v43, s[10:11] offset:3072
	global_load_dwordx4 v[12:15], v42, s[10:11] offset:-512
	s_add_u32 s10, s14, 0x7f00000
	s_addc_u32 s11, s15, 0
	global_load_dwordx4 v[16:19], v43, s[10:11] offset:3072
	global_load_dwordx4 v[20:23], v42, s[10:11] offset:-512
	s_waitcnt vmcnt(4)
	v_cndmask_b32_e64 v4, 0, v4, s[26:27]
	v_cndmask_b32_e64 v5, 0, v5, s[26:27]
	v_cndmask_b32_e64 v6, 0, v6, s[26:27]
	v_cndmask_b32_e64 v7, 0, v7, s[26:27]
	v_lshlrev_b32_e32 v48, 16, v0
	v_and_b32_e32 v49, 0xffff0000, v0
	v_lshlrev_b32_e32 v56, 16, v4
	v_and_b32_e32 v57, 0xffff0000, v4
	v_lshlrev_b32_e32 v50, 16, v1
	v_and_b32_e32 v51, 0xffff0000, v1
	v_lshlrev_b32_e32 v58, 16, v5
	v_and_b32_e32 v59, 0xffff0000, v5
	v_lshlrev_b32_e32 v52, 16, v2
	v_and_b32_e32 v53, 0xffff0000, v2
	v_lshlrev_b32_e32 v60, 16, v6
	v_and_b32_e32 v61, 0xffff0000, v6
	v_lshlrev_b32_e32 v54, 16, v3
	v_and_b32_e32 v55, 0xffff0000, v3
	v_lshlrev_b32_e32 v62, 16, v7
	v_and_b32_e32 v63, 0xffff0000, v7
	v_sub_f32_e32 v56, v56, v48
	v_sub_f32_e32 v57, v57, v49
	v_sub_f32_e32 v58, v58, v50
	v_sub_f32_e32 v59, v59, v51
	v_sub_f32_e32 v60, v60, v52
	v_sub_f32_e32 v61, v61, v53
	v_sub_f32_e32 v62, v62, v54
	v_sub_f32_e32 v63, v63, v55
	v_fmac_f32_e32 v48, v32, v56
	v_fmac_f32_e32 v49, v33, v57
	v_fmac_f32_e32 v50, v34, v58
	v_fmac_f32_e32 v51, v35, v59
	v_fmac_f32_e32 v52, v36, v60
	v_fmac_f32_e32 v53, v37, v61
	v_fmac_f32_e32 v54, v38, v62
	v_fmac_f32_e32 v55, v39, v63
	s_mov_b64 exec, s[28:29]
	v_add_f32_e32 v56, v48, v48
	v_add_f32_e32 v57, v49, v49
	v_add_f32_e32 v58, v50, v50
	v_add_f32_e32 v59, v51, v51
	v_add_f32_e32 v60, v52, v52
	v_add_f32_e32 v61, v53, v53
	v_add_f32_e32 v62, v54, v54
	v_add_f32_e32 v63, v55, v55
	v_mul_f32_e32 v56, 0x3fb8aa3b, v56
	v_mul_f32_e32 v57, 0x3fb8aa3b, v57
	v_mul_f32_e32 v58, 0x3fb8aa3b, v58
	v_mul_f32_e32 v59, 0x3fb8aa3b, v59
	v_mul_f32_e32 v60, 0x3fb8aa3b, v60
	v_mul_f32_e32 v61, 0x3fb8aa3b, v61
	v_mul_f32_e32 v62, 0x3fb8aa3b, v62
	v_mul_f32_e32 v63, 0x3fb8aa3b, v63
	v_exp_f32_e32 v56, v56
	v_exp_f32_e32 v57, v57
	v_exp_f32_e32 v58, v58
	v_exp_f32_e32 v59, v59
	v_exp_f32_e32 v60, v60
	v_exp_f32_e32 v61, v61
	v_exp_f32_e32 v62, v62
	v_exp_f32_e32 v63, v63
	v_add_f32_e32 v56, 1.0, v56
	v_add_f32_e32 v57, 1.0, v57
	v_add_f32_e32 v58, 1.0, v58
	v_add_f32_e32 v59, 1.0, v59
	v_add_f32_e32 v60, 1.0, v60
	v_add_f32_e32 v61, 1.0, v61
	v_add_f32_e32 v62, 1.0, v62
	v_add_f32_e32 v63, 1.0, v63
	v_rcp_f32_e32 v56, v56
	v_rcp_f32_e32 v57, v57
	v_rcp_f32_e32 v58, v58
	v_rcp_f32_e32 v59, v59
	v_rcp_f32_e32 v60, v60
	v_rcp_f32_e32 v61, v61
	v_rcp_f32_e32 v62, v62
	v_rcp_f32_e32 v63, v63
	v_fma_f32 v48, v56, -2.0, 1.0
	v_fma_f32 v49, v57, -2.0, 1.0
	v_fma_f32 v50, v58, -2.0, 1.0
	v_fma_f32 v51, v59, -2.0, 1.0
	v_fma_f32 v52, v60, -2.0, 1.0
	v_fma_f32 v53, v61, -2.0, 1.0
	v_fma_f32 v54, v62, -2.0, 1.0
	v_fma_f32 v55, v63, -2.0, 1.0
	s_mov_b64 exec, s[30:31]
	v_mul_f32_e32 v56, 0xbfb8aa3b, v48
	v_mul_f32_e32 v57, 0xbfb8aa3b, v49
	v_mul_f32_e32 v58, 0xbfb8aa3b, v50
	v_mul_f32_e32 v59, 0xbfb8aa3b, v51
	v_mul_f32_e32 v60, 0xbfb8aa3b, v52
	v_mul_f32_e32 v61, 0xbfb8aa3b, v53
	v_mul_f32_e32 v62, 0xbfb8aa3b, v54
	v_mul_f32_e32 v63, 0xbfb8aa3b, v55
	v_exp_f32_e32 v56, v56
	v_exp_f32_e32 v57, v57
	v_exp_f32_e32 v58, v58
	v_exp_f32_e32 v59, v59
	v_exp_f32_e32 v60, v60
	v_exp_f32_e32 v61, v61
	v_exp_f32_e32 v62, v62
	v_exp_f32_e32 v63, v63
	v_add_f32_e32 v56, 1.0, v56
	v_add_f32_e32 v57, 1.0, v57
	v_add_f32_e32 v58, 1.0, v58
	v_add_f32_e32 v59, 1.0, v59
	v_add_f32_e32 v60, 1.0, v60
	v_add_f32_e32 v61, 1.0, v61
	v_add_f32_e32 v62, 1.0, v62
	v_add_f32_e32 v63, 1.0, v63
	v_rcp_f32_e32 v48, v56
	v_rcp_f32_e32 v49, v57
	v_rcp_f32_e32 v50, v58
	v_rcp_f32_e32 v51, v59
	v_rcp_f32_e32 v52, v60
	v_rcp_f32_e32 v53, v61
	v_rcp_f32_e32 v54, v62
	v_rcp_f32_e32 v55, v63
	s_mov_b64 exec, -1
	v_cvt_pk_bf16_f32 v64, v48, v49
	v_cvt_pk_bf16_f32 v65, v50, v51
	v_cvt_pk_bf16_f32 v66, v52, v53
	v_cvt_pk_bf16_f32 v67, v54, v55
	s_add_u32 s12, s14, 0xeb00000
	s_addc_u32 s13, s15, 0
	global_store_dwordx4 v44, v[64:67], s[12:13]
	s_add_u32 s10, s14, 0x9d00000
	s_addc_u32 s11, s15, 0
	global_load_dwordx4 v[24:27], v43, s[10:11] offset:3072
	global_load_dwordx4 v[28:31], v42, s[10:11] offset:-512
	s_waitcnt vmcnt(5)
	v_cndmask_b32_e64 v12, 0, v12, s[26:27]
	v_cndmask_b32_e64 v13, 0, v13, s[26:27]
	v_cndmask_b32_e64 v14, 0, v14, s[26:27]
	v_cndmask_b32_e64 v15, 0, v15, s[26:27]
	v_lshlrev_b32_e32 v48, 16, v8
	v_and_b32_e32 v49, 0xffff0000, v8
	v_lshlrev_b32_e32 v56, 16, v12
	v_and_b32_e32 v57, 0xffff0000, v12
	v_lshlrev_b32_e32 v50, 16, v9
	v_and_b32_e32 v51, 0xffff0000, v9
	v_lshlrev_b32_e32 v58, 16, v13
	v_and_b32_e32 v59, 0xffff0000, v13
	v_lshlrev_b32_e32 v52, 16, v10
	v_and_b32_e32 v53, 0xffff0000, v10
	v_lshlrev_b32_e32 v60, 16, v14
	v_and_b32_e32 v61, 0xffff0000, v14
	v_lshlrev_b32_e32 v54, 16, v11
	v_and_b32_e32 v55, 0xffff0000, v11
	v_lshlrev_b32_e32 v62, 16, v15
	v_and_b32_e32 v63, 0xffff0000, v15
	v_sub_f32_e32 v56, v56, v48
	v_sub_f32_e32 v57, v57, v49
	v_sub_f32_e32 v58, v58, v50
	v_sub_f32_e32 v59, v59, v51
	v_sub_f32_e32 v60, v60, v52
	v_sub_f32_e32 v61, v61, v53
	v_sub_f32_e32 v62, v62, v54
	v_sub_f32_e32 v63, v63, v55
	v_fmac_f32_e32 v48, v32, v56
	v_fmac_f32_e32 v49, v33, v57
	v_fmac_f32_e32 v50, v34, v58
	v_fmac_f32_e32 v51, v35, v59
	v_fmac_f32_e32 v52, v36, v60
	v_fmac_f32_e32 v53, v37, v61
	v_fmac_f32_e32 v54, v38, v62
	v_fmac_f32_e32 v55, v39, v63
	s_mov_b64 exec, s[28:29]
	v_add_f32_e32 v56, v48, v48
	v_add_f32_e32 v57, v49, v49
	v_add_f32_e32 v58, v50, v50
	v_add_f32_e32 v59, v51, v51
	v_add_f32_e32 v60, v52, v52
	v_add_f32_e32 v61, v53, v53
	v_add_f32_e32 v62, v54, v54
	v_add_f32_e32 v63, v55, v55
	v_mul_f32_e32 v56, 0x3fb8aa3b, v56
	v_mul_f32_e32 v57, 0x3fb8aa3b, v57
	v_mul_f32_e32 v58, 0x3fb8aa3b, v58
	v_mul_f32_e32 v59, 0x3fb8aa3b, v59
	v_mul_f32_e32 v60, 0x3fb8aa3b, v60
	v_mul_f32_e32 v61, 0x3fb8aa3b, v61
	v_mul_f32_e32 v62, 0x3fb8aa3b, v62
	v_mul_f32_e32 v63, 0x3fb8aa3b, v63
	v_exp_f32_e32 v56, v56
	v_exp_f32_e32 v57, v57
	v_exp_f32_e32 v58, v58
	v_exp_f32_e32 v59, v59
	v_exp_f32_e32 v60, v60
	v_exp_f32_e32 v61, v61
	v_exp_f32_e32 v62, v62
	v_exp_f32_e32 v63, v63
	v_add_f32_e32 v56, 1.0, v56
	v_add_f32_e32 v57, 1.0, v57
	v_add_f32_e32 v58, 1.0, v58
	v_add_f32_e32 v59, 1.0, v59
	v_add_f32_e32 v60, 1.0, v60
	v_add_f32_e32 v61, 1.0, v61
	v_add_f32_e32 v62, 1.0, v62
	v_add_f32_e32 v63, 1.0, v63
	v_rcp_f32_e32 v56, v56
	v_rcp_f32_e32 v57, v57
	v_rcp_f32_e32 v58, v58
	v_rcp_f32_e32 v59, v59
	v_rcp_f32_e32 v60, v60
	v_rcp_f32_e32 v61, v61
	v_rcp_f32_e32 v62, v62
	v_rcp_f32_e32 v63, v63
	v_fma_f32 v48, v56, -2.0, 1.0
	v_fma_f32 v49, v57, -2.0, 1.0
	v_fma_f32 v50, v58, -2.0, 1.0
	v_fma_f32 v51, v59, -2.0, 1.0
	v_fma_f32 v52, v60, -2.0, 1.0
	v_fma_f32 v53, v61, -2.0, 1.0
	v_fma_f32 v54, v62, -2.0, 1.0
	v_fma_f32 v55, v63, -2.0, 1.0
	s_mov_b64 exec, s[30:31]
	v_mul_f32_e32 v56, 0xbfb8aa3b, v48
	v_mul_f32_e32 v57, 0xbfb8aa3b, v49
	v_mul_f32_e32 v58, 0xbfb8aa3b, v50
	v_mul_f32_e32 v59, 0xbfb8aa3b, v51
	v_mul_f32_e32 v60, 0xbfb8aa3b, v52
	v_mul_f32_e32 v61, 0xbfb8aa3b, v53
	v_mul_f32_e32 v62, 0xbfb8aa3b, v54
	v_mul_f32_e32 v63, 0xbfb8aa3b, v55
	v_exp_f32_e32 v56, v56
	v_exp_f32_e32 v57, v57
	v_exp_f32_e32 v58, v58
	v_exp_f32_e32 v59, v59
	v_exp_f32_e32 v60, v60
	v_exp_f32_e32 v61, v61
	v_exp_f32_e32 v62, v62
	v_exp_f32_e32 v63, v63
	v_add_f32_e32 v56, 1.0, v56
	v_add_f32_e32 v57, 1.0, v57
	v_add_f32_e32 v58, 1.0, v58
	v_add_f32_e32 v59, 1.0, v59
	v_add_f32_e32 v60, 1.0, v60
	v_add_f32_e32 v61, 1.0, v61
	v_add_f32_e32 v62, 1.0, v62
	v_add_f32_e32 v63, 1.0, v63
	v_rcp_f32_e32 v48, v56
	v_rcp_f32_e32 v49, v57
	v_rcp_f32_e32 v50, v58
	v_rcp_f32_e32 v51, v59
	v_rcp_f32_e32 v52, v60
	v_rcp_f32_e32 v53, v61
	v_rcp_f32_e32 v54, v62
	v_rcp_f32_e32 v55, v63
	s_mov_b64 exec, -1
	v_cvt_pk_bf16_f32 v68, v48, v49
	v_cvt_pk_bf16_f32 v69, v50, v51
	v_cvt_pk_bf16_f32 v70, v52, v53
	v_cvt_pk_bf16_f32 v71, v54, v55
	s_add_u32 s12, s14, 0xed00000
	s_addc_u32 s13, s15, 0
	global_store_dwordx4 v44, v[68:71], s[12:13]
	s_waitcnt vmcnt(4)
	v_cndmask_b32_e64 v20, 0, v20, s[26:27]
	v_cndmask_b32_e64 v21, 0, v21, s[26:27]
	v_cndmask_b32_e64 v22, 0, v22, s[26:27]
	v_cndmask_b32_e64 v23, 0, v23, s[26:27]
	v_lshlrev_b32_e32 v48, 16, v16
	v_and_b32_e32 v49, 0xffff0000, v16
	v_lshlrev_b32_e32 v56, 16, v20
	v_and_b32_e32 v57, 0xffff0000, v20
	v_lshlrev_b32_e32 v50, 16, v17
	v_and_b32_e32 v51, 0xffff0000, v17
	v_lshlrev_b32_e32 v58, 16, v21
	v_and_b32_e32 v59, 0xffff0000, v21
	v_lshlrev_b32_e32 v52, 16, v18
	v_and_b32_e32 v53, 0xffff0000, v18
	v_lshlrev_b32_e32 v60, 16, v22
	v_and_b32_e32 v61, 0xffff0000, v22
	v_lshlrev_b32_e32 v54, 16, v19
	v_and_b32_e32 v55, 0xffff0000, v19
	v_lshlrev_b32_e32 v62, 16, v23
	v_and_b32_e32 v63, 0xffff0000, v23
	v_sub_f32_e32 v56, v56, v48
	v_sub_f32_e32 v57, v57, v49
	v_sub_f32_e32 v58, v58, v50
	v_sub_f32_e32 v59, v59, v51
	v_sub_f32_e32 v60, v60, v52
	v_sub_f32_e32 v61, v61, v53
	v_sub_f32_e32 v62, v62, v54
	v_sub_f32_e32 v63, v63, v55
	v_fmac_f32_e32 v48, v32, v56
	v_fmac_f32_e32 v49, v33, v57
	v_fmac_f32_e32 v50, v34, v58
	v_fmac_f32_e32 v51, v35, v59
	v_fmac_f32_e32 v52, v36, v60
	v_fmac_f32_e32 v53, v37, v61
	v_fmac_f32_e32 v54, v38, v62
	v_fmac_f32_e32 v55, v39, v63
	s_mov_b64 exec, s[28:29]
	v_add_f32_e32 v56, v48, v48
	v_add_f32_e32 v57, v49, v49
	v_add_f32_e32 v58, v50, v50
	v_add_f32_e32 v59, v51, v51
	v_add_f32_e32 v60, v52, v52
	v_add_f32_e32 v61, v53, v53
	v_add_f32_e32 v62, v54, v54
	v_add_f32_e32 v63, v55, v55
	v_mul_f32_e32 v56, 0x3fb8aa3b, v56
	v_mul_f32_e32 v57, 0x3fb8aa3b, v57
	v_mul_f32_e32 v58, 0x3fb8aa3b, v58
	v_mul_f32_e32 v59, 0x3fb8aa3b, v59
	v_mul_f32_e32 v60, 0x3fb8aa3b, v60
	v_mul_f32_e32 v61, 0x3fb8aa3b, v61
	v_mul_f32_e32 v62, 0x3fb8aa3b, v62
	v_mul_f32_e32 v63, 0x3fb8aa3b, v63
	v_exp_f32_e32 v56, v56
	v_exp_f32_e32 v57, v57
	v_exp_f32_e32 v58, v58
	v_exp_f32_e32 v59, v59
	v_exp_f32_e32 v60, v60
	v_exp_f32_e32 v61, v61
	v_exp_f32_e32 v62, v62
	v_exp_f32_e32 v63, v63
	v_add_f32_e32 v56, 1.0, v56
	v_add_f32_e32 v57, 1.0, v57
	v_add_f32_e32 v58, 1.0, v58
	v_add_f32_e32 v59, 1.0, v59
	v_add_f32_e32 v60, 1.0, v60
	v_add_f32_e32 v61, 1.0, v61
	v_add_f32_e32 v62, 1.0, v62
	v_add_f32_e32 v63, 1.0, v63
	v_rcp_f32_e32 v56, v56
	v_rcp_f32_e32 v57, v57
	v_rcp_f32_e32 v58, v58
	v_rcp_f32_e32 v59, v59
	v_rcp_f32_e32 v60, v60
	v_rcp_f32_e32 v61, v61
	v_rcp_f32_e32 v62, v62
	v_rcp_f32_e32 v63, v63
	v_fma_f32 v48, v56, -2.0, 1.0
	v_fma_f32 v49, v57, -2.0, 1.0
	v_fma_f32 v50, v58, -2.0, 1.0
	v_fma_f32 v51, v59, -2.0, 1.0
	v_fma_f32 v52, v60, -2.0, 1.0
	v_fma_f32 v53, v61, -2.0, 1.0
	v_fma_f32 v54, v62, -2.0, 1.0
	v_fma_f32 v55, v63, -2.0, 1.0
	s_mov_b64 exec, s[30:31]
	v_mul_f32_e32 v56, 0xbfb8aa3b, v48
	v_mul_f32_e32 v57, 0xbfb8aa3b, v49
	v_mul_f32_e32 v58, 0xbfb8aa3b, v50
	v_mul_f32_e32 v59, 0xbfb8aa3b, v51
	v_mul_f32_e32 v60, 0xbfb8aa3b, v52
	v_mul_f32_e32 v61, 0xbfb8aa3b, v53
	v_mul_f32_e32 v62, 0xbfb8aa3b, v54
	v_mul_f32_e32 v63, 0xbfb8aa3b, v55
	v_exp_f32_e32 v56, v56
	v_exp_f32_e32 v57, v57
	v_exp_f32_e32 v58, v58
	v_exp_f32_e32 v59, v59
	v_exp_f32_e32 v60, v60
	v_exp_f32_e32 v61, v61
	v_exp_f32_e32 v62, v62
	v_exp_f32_e32 v63, v63
	v_add_f32_e32 v56, 1.0, v56
	v_add_f32_e32 v57, 1.0, v57
	v_add_f32_e32 v58, 1.0, v58
	v_add_f32_e32 v59, 1.0, v59
	v_add_f32_e32 v60, 1.0, v60
	v_add_f32_e32 v61, 1.0, v61
	v_add_f32_e32 v62, 1.0, v62
	v_add_f32_e32 v63, 1.0, v63
	v_rcp_f32_e32 v48, v56
	v_rcp_f32_e32 v49, v57
	v_rcp_f32_e32 v50, v58
	v_rcp_f32_e32 v51, v59
	v_rcp_f32_e32 v52, v60
	v_rcp_f32_e32 v53, v61
	v_rcp_f32_e32 v54, v62
	v_rcp_f32_e32 v55, v63
	s_mov_b64 exec, -1
	v_cvt_pk_bf16_f32 v72, v48, v49
	v_cvt_pk_bf16_f32 v73, v50, v51
	v_cvt_pk_bf16_f32 v74, v52, v53
	v_cvt_pk_bf16_f32 v75, v54, v55
	s_add_u32 s12, s14, 0xef00000
	s_addc_u32 s13, s15, 0
	global_store_dwordx4 v44, v[72:75], s[12:13]
	s_waitcnt vmcnt(2)
	v_cndmask_b32_e64 v28, 0, v28, s[26:27]
	v_cndmask_b32_e64 v29, 0, v29, s[26:27]
	v_cndmask_b32_e64 v30, 0, v30, s[26:27]
	v_cndmask_b32_e64 v31, 0, v31, s[26:27]
	v_lshlrev_b32_e32 v48, 16, v24
	v_and_b32_e32 v49, 0xffff0000, v24
	v_lshlrev_b32_e32 v56, 16, v28
	v_and_b32_e32 v57, 0xffff0000, v28
	v_lshlrev_b32_e32 v50, 16, v25
	v_and_b32_e32 v51, 0xffff0000, v25
	v_lshlrev_b32_e32 v58, 16, v29
	v_and_b32_e32 v59, 0xffff0000, v29
	v_lshlrev_b32_e32 v52, 16, v26
	v_and_b32_e32 v53, 0xffff0000, v26
	v_lshlrev_b32_e32 v60, 16, v30
	v_and_b32_e32 v61, 0xffff0000, v30
	v_lshlrev_b32_e32 v54, 16, v27
	v_and_b32_e32 v55, 0xffff0000, v27
	v_lshlrev_b32_e32 v62, 16, v31
	v_and_b32_e32 v63, 0xffff0000, v31
	v_sub_f32_e32 v56, v56, v48
	v_sub_f32_e32 v57, v57, v49
	v_sub_f32_e32 v58, v58, v50
	v_sub_f32_e32 v59, v59, v51
	v_sub_f32_e32 v60, v60, v52
	v_sub_f32_e32 v61, v61, v53
	v_sub_f32_e32 v62, v62, v54
	v_sub_f32_e32 v63, v63, v55
	v_fmac_f32_e32 v48, v32, v56
	v_fmac_f32_e32 v49, v33, v57
	v_fmac_f32_e32 v50, v34, v58
	v_fmac_f32_e32 v51, v35, v59
	v_fmac_f32_e32 v52, v36, v60
	v_fmac_f32_e32 v53, v37, v61
	v_fmac_f32_e32 v54, v38, v62
	v_fmac_f32_e32 v55, v39, v63
	s_mov_b64 exec, s[28:29]
	v_add_f32_e32 v56, v48, v48
	v_add_f32_e32 v57, v49, v49
	v_add_f32_e32 v58, v50, v50
	v_add_f32_e32 v59, v51, v51
	v_add_f32_e32 v60, v52, v52
	v_add_f32_e32 v61, v53, v53
	v_add_f32_e32 v62, v54, v54
	v_add_f32_e32 v63, v55, v55
	v_mul_f32_e32 v56, 0x3fb8aa3b, v56
	v_mul_f32_e32 v57, 0x3fb8aa3b, v57
	v_mul_f32_e32 v58, 0x3fb8aa3b, v58
	v_mul_f32_e32 v59, 0x3fb8aa3b, v59
	v_mul_f32_e32 v60, 0x3fb8aa3b, v60
	v_mul_f32_e32 v61, 0x3fb8aa3b, v61
	v_mul_f32_e32 v62, 0x3fb8aa3b, v62
	v_mul_f32_e32 v63, 0x3fb8aa3b, v63
	v_exp_f32_e32 v56, v56
	v_exp_f32_e32 v57, v57
	v_exp_f32_e32 v58, v58
	v_exp_f32_e32 v59, v59
	v_exp_f32_e32 v60, v60
	v_exp_f32_e32 v61, v61
	v_exp_f32_e32 v62, v62
	v_exp_f32_e32 v63, v63
	v_add_f32_e32 v56, 1.0, v56
	v_add_f32_e32 v57, 1.0, v57
	v_add_f32_e32 v58, 1.0, v58
	v_add_f32_e32 v59, 1.0, v59
	v_add_f32_e32 v60, 1.0, v60
	v_add_f32_e32 v61, 1.0, v61
	v_add_f32_e32 v62, 1.0, v62
	v_add_f32_e32 v63, 1.0, v63
	v_rcp_f32_e32 v56, v56
	v_rcp_f32_e32 v57, v57
	v_rcp_f32_e32 v58, v58
	v_rcp_f32_e32 v59, v59
	v_rcp_f32_e32 v60, v60
	v_rcp_f32_e32 v61, v61
	v_rcp_f32_e32 v62, v62
	v_rcp_f32_e32 v63, v63
	v_fma_f32 v48, v56, -2.0, 1.0
	v_fma_f32 v49, v57, -2.0, 1.0
	v_fma_f32 v50, v58, -2.0, 1.0
	v_fma_f32 v51, v59, -2.0, 1.0
	v_fma_f32 v52, v60, -2.0, 1.0
	v_fma_f32 v53, v61, -2.0, 1.0
	v_fma_f32 v54, v62, -2.0, 1.0
	v_fma_f32 v55, v63, -2.0, 1.0
	s_mov_b64 exec, s[30:31]
	v_mul_f32_e32 v56, 0xbfb8aa3b, v48
	v_mul_f32_e32 v57, 0xbfb8aa3b, v49
	v_mul_f32_e32 v58, 0xbfb8aa3b, v50
	v_mul_f32_e32 v59, 0xbfb8aa3b, v51
	v_mul_f32_e32 v60, 0xbfb8aa3b, v52
	v_mul_f32_e32 v61, 0xbfb8aa3b, v53
	v_mul_f32_e32 v62, 0xbfb8aa3b, v54
	v_mul_f32_e32 v63, 0xbfb8aa3b, v55
	v_exp_f32_e32 v56, v56
	v_exp_f32_e32 v57, v57
	v_exp_f32_e32 v58, v58
	v_exp_f32_e32 v59, v59
	v_exp_f32_e32 v60, v60
	v_exp_f32_e32 v61, v61
	v_exp_f32_e32 v62, v62
	v_exp_f32_e32 v63, v63
	v_add_f32_e32 v56, 1.0, v56
	v_add_f32_e32 v57, 1.0, v57
	v_add_f32_e32 v58, 1.0, v58
	v_add_f32_e32 v59, 1.0, v59
	v_add_f32_e32 v60, 1.0, v60
	v_add_f32_e32 v61, 1.0, v61
	v_add_f32_e32 v62, 1.0, v62
	v_add_f32_e32 v63, 1.0, v63
	v_rcp_f32_e32 v48, v56
	v_rcp_f32_e32 v49, v57
	v_rcp_f32_e32 v50, v58
	v_rcp_f32_e32 v51, v59
	v_rcp_f32_e32 v52, v60
	v_rcp_f32_e32 v53, v61
	v_rcp_f32_e32 v54, v62
	v_rcp_f32_e32 v55, v63
	s_mov_b64 exec, -1
	v_cvt_pk_bf16_f32 v76, v48, v49
	v_cvt_pk_bf16_f32 v77, v50, v51
	v_cvt_pk_bf16_f32 v78, v52, v53
	v_cvt_pk_bf16_f32 v79, v54, v55
	s_add_u32 s12, s14, 0xf100000
	s_addc_u32 s13, s15, 0
	global_store_dwordx4 v44, v[76:79], s[12:13]
	s_mov_b64 s[6:7], 0
